# wi 11/21 + kernel prologue: XCD ticket atomic issued together with the pointer-table load (one round trip instead of two)
# speedup vs baseline: 1.0021x; 1.0021x over previous
.LBB0_5:
	v_lshlrev_b32_e32 v4, 3, v0
	global_load_dwordx2 v[2:3], v4, s[0:1]
	v_add_u32_e32 v4, 0, v4
	v_add_u32_e32 v4, 0x23080, v4
	s_waitcnt lgkmcnt(0)
	s_add_u32 s46, s42, 0x4000
	s_addc_u32 s47, s43, 0
	s_getreg_b32 s8, hwreg(HW_REG_XCC_ID, 0, 4)
	s_and_b32 s8, s8, 15
	s_lshl_b32 s8, s8, 8
	s_mov_b64 s[10:11], exec
	s_mov_b64 exec, 1
	v_mov_b32_e32 v5, s8
	v_mov_b32_e32 v6, 1
	global_atomic_add v5, v5, v6, s[46:47] offset:1024 sc0
	s_mov_b64 exec, s[10:11]
	s_waitcnt vmcnt(0)
	ds_write_b64 v4, v[2:3]
.LBB0_6:
	s_or_b64 exec, exec, s[4:5]
	s_waitcnt lgkmcnt(0)
	s_barrier
	s_add_u32 s46, s42, 0x4000
	s_getreg_b32 s4, hwreg(HW_REG_XCC_ID, 0, 4)
	s_addc_u32 s47, s43, 0
	s_and_b32 s33, s4, 15
	v_cmp_eq_u32_e64 s[36:37], 0, v0
	s_and_saveexec_b64 s[4:5], s[36:37]
	s_cbranch_execz .LBB0_10
	s_mov_b64 s[8:9], exec
	v_mbcnt_lo_u32_b32 v2, s8, 0
	v_mbcnt_hi_u32_b32 v2, s9, v2
	v_cmp_eq_u32_e32 vcc, 0, v2
	s_and_saveexec_b64 s[6:7], vcc
	s_cbranch_execz .LBB0_9
	s_lshl_b32 s10, s33, 8
	s_bcnt1_i32_b64 s8, s[8:9]
	v_mov_b32_e32 v3, s10
	v_mov_b32_e32 v4, s8
	v_mov_b32_e32 v3, v5
